# P1 weight-conversion tail: third-round items dealt 4 per workgroup over 80 workgroups instead of 8 per workgroup over 40
# speedup vs baseline: 1.0095x; 1.0064x over previous
; __device__ __forceinline__ void convert_weights(const Args& args, int first, int last, int worker, int nworkers, int lane) {
;     ...
;     for (;;) {
;         const int nx = it + nworkers; const bool more = nx < last;
;         WItem nxt = cur; f32x4 vn[WR];
;         if (more) { nxt = witem_decode(args, nx, lane); witem_load(nxt, vn); }
;         witem_store(cur, v);
;         if (!more) break;
; #pragma unroll
;         for (int j = 0; j < WR; ++j) v[j] = vn[j];
;         cur = nxt; it = nx;
; __global__ void __launch_bounds__(NWAVES * 64, 2) fwd_kernel(Args args) {
;     ...
;         if (G == 256 && bx >= 128) {
;             int tl_ = threadIdx.x; asm volatile("" : "+v"(tl_));
;             convert_weights(args, WI_P1 + WI_OUT, WI_ALL, (bx - 128) * NWAVES + wave, 128 * NWAVES, tl_ & 63);
;         }
.LBB0_429:
	s_add_i32 s28, s33, 0x400
	s_cmpk_gt_i32 s33, 0x8ff
	s_cselect_b64 s[8:9], -1, 0
	s_cmpk_lt_i32 s33, 0x7c0
	s_cbranch_scc1 .Lcv3_keep
	s_cmpk_gt_i32 s33, 0xbbf
	s_cbranch_scc1 .Lcv3_keep
	s_add_i32 s98, s33, 0xfffff840
	s_lshr_b32 s99, s98, 1
	s_and_b32 s99, s99, 0xfffffffc
	s_and_b32 s28, s98, 3
	s_add_i32 s28, s28, s99
	s_addk_i32 s28, 0xbc0
	s_add_i32 s33, s28, 0xfffffc00
	s_and_b32 s99, s98, 4
	s_cselect_b32 s99, 1, 0
	s_cmpk_gt_u32 s98, 0x27f
	s_cselect_b32 s99, 1, s99
	s_cmp_lg_u32 s99, 0
	s_cselect_b64 s[8:9], -1, 0
.Lcv3_keep:
	s_and_b64 vcc, exec, s[8:9]
	s_mov_b32 s24, s2
	v_mov_b32_e32 v132, v130
	s_cbranch_vccnz .LBB0_445
	s_cmpk_lt_i32 s33, 0xfe80
	s_cbranch_scc1 .LBB0_438
	s_cmpk_gt_u32 s28, 0x2bf
	s_cbranch_scc0 .LBB0_439
	s_cmpk_gt_u32 s28, 0x3bf
	s_cbranch_scc0 .LBB0_440
	s_cmpk_gt_u32 s28, 0x93f
	s_cbranch_scc0 .LBB0_449
	s_cmpk_gt_u32 s28, 0xbff
	s_cbranch_scc0 .LBB0_451
	v_readlane_b32 s52, v254, 2
	v_readlane_b32 s62, v254, 12
	v_readlane_b32 s63, v254, 13
	v_readlane_b32 s64, v254, 14
	v_readlane_b32 s65, v254, 15
	s_add_i32 s3, s33, 0xfffff800
	v_readlane_b32 s53, v254, 3
	v_readlane_b32 s54, v254, 4
	v_readlane_b32 s55, v254, 5
	v_readlane_b32 s56, v254, 6
	v_readlane_b32 s57, v254, 7
	v_readlane_b32 s58, v254, 8
	v_readlane_b32 s59, v254, 9
	v_readlane_b32 s60, v254, 10
	v_readlane_b32 s61, v254, 11
	v_readlane_b32 s66, v254, 16
	v_readlane_b32 s67, v254, 17
	s_mov_b64 s[6:7], s[62:63]
	s_mov_b64 s[40:41], s[64:65]
	s_cbranch_execz .LBB0_452
	s_movk_i32 s30, 0x400
	s_mov_b32 s29, 0
	s_mov_b64 s[36:37], s[94:95]
	s_cbranch_execz .LBB0_450
